# MO8+TRIM+Z0 (srcC=0 first iteration, no accumulator zeroing) + OW (first-iteration vmcnt relaxation)
# speedup vs baseline: 1.0017x; 1.0017x over previous
.Low_2_done:
	s_waitcnt lgkmcnt(0)
	s_cmp_eq_u32 s48, -2
	s_cbranch_scc1 .Lz0_0_0
	s_setprio 1
	s_barrier
	v_mfma_f32_16x16x32_bf16 v[126:129], v[140:143], v[194:197], v[126:129]
	v_mfma_f32_16x16x32_bf16 v[126:129], v[148:151], v[198:201], v[126:129]
	v_mfma_f32_16x16x32_bf16 v[118:121], v[148:151], v[206:209], v[118:121]
	v_mfma_f32_16x16x32_bf16 v[118:121], v[140:143], v[202:205], v[118:121]
	v_mfma_f32_16x16x32_bf16 v[102:105], v[140:143], v[228:231], v[102:105]
	v_mfma_f32_16x16x32_bf16 v[102:105], v[148:151], v[232:235], v[102:105]
	v_mfma_f32_16x16x32_bf16 v[86:89], v[148:151], v[240:243], v[86:89]
	v_mfma_f32_16x16x32_bf16 v[86:89], v[140:143], v[236:239], v[86:89]
	v_mfma_f32_16x16x32_bf16 v[78:81], v[152:155], v[236:239], v[78:81]
	v_mfma_f32_16x16x32_bf16 v[78:81], v[156:159], v[240:243], v[78:81]
	v_mfma_f32_16x16x32_bf16 v[94:97], v[156:159], v[232:235], v[94:97]
	v_mfma_f32_16x16x32_bf16 v[94:97], v[152:155], v[228:231], v[94:97]
	v_mfma_f32_16x16x32_bf16 v[110:113], v[152:155], v[202:205], v[110:113]
	v_mfma_f32_16x16x32_bf16 v[110:113], v[156:159], v[206:209], v[110:113]
	v_mfma_f32_16x16x32_bf16 v[122:125], v[156:159], v[198:201], v[122:125]
	v_mfma_f32_16x16x32_bf16 v[122:125], v[152:155], v[194:197], v[122:125]
	v_mfma_f32_16x16x32_bf16 v[114:117], v[160:163], v[194:197], v[114:117]
	v_mfma_f32_16x16x32_bf16 v[114:117], v[164:167], v[198:201], v[114:117]
	v_mfma_f32_16x16x32_bf16 v[98:101], v[164:167], v[206:209], v[98:101]
	v_mfma_f32_16x16x32_bf16 v[98:101], v[160:163], v[202:205], v[98:101]
	v_mfma_f32_16x16x32_bf16 v[82:85], v[160:163], v[228:231], v[82:85]
	v_mfma_f32_16x16x32_bf16 v[82:85], v[164:167], v[232:235], v[82:85]
	v_mfma_f32_16x16x32_bf16 v[70:73], v[164:167], v[240:243], v[70:73]
	v_mfma_f32_16x16x32_bf16 v[70:73], v[160:163], v[236:239], v[70:73]
	v_mfma_f32_16x16x32_bf16 v[66:69], v[168:171], v[236:239], v[66:69]
	v_mfma_f32_16x16x32_bf16 v[66:69], v[190:193], v[240:243], v[66:69]
	v_mfma_f32_16x16x32_bf16 v[74:77], v[190:193], v[232:235], v[74:77]
	v_mfma_f32_16x16x32_bf16 v[74:77], v[168:171], v[228:231], v[74:77]
	v_mfma_f32_16x16x32_bf16 v[90:93], v[168:171], v[202:205], v[90:93]
	v_mfma_f32_16x16x32_bf16 v[90:93], v[190:193], v[206:209], v[90:93]
	v_mfma_f32_16x16x32_bf16 v[106:109], v[190:193], v[198:201], v[106:109]
	v_mfma_f32_16x16x32_bf16 v[106:109], v[168:171], v[194:197], v[106:109]
	s_barrier
	s_setprio 0
.Lz0_0_0_ret:
	s_add_i32 s49, s49, s26
	v_lshl_add_u64 v[172:173], s[22:23], 0, v[0:1]
	s_mov_b32 m0, s49
	ds_read_b128 v[194:197], v147 offset:16384
	ds_read_b128 v[198:201], v147 offset:17408
	ds_read_b128 v[202:205], v147 offset:18432
	ds_read_b128 v[206:209], v147 offset:19456
	ds_read_b128 v[228:231], v147 offset:20480
	ds_read_b128 v[232:235], v147 offset:21504
	ds_read_b128 v[236:239], v147 offset:22528
	ds_read_b128 v[240:243], v147 offset:23552
	global_load_lds_dwordx4 v[172:173], off
	s_add_i32 m0, s49, 0x2000
	s_add_u32 s50, s22, 0x100000
	v_lshl_add_u64 v[178:179], s[22:23], 0, v[130:131]
	s_addc_u32 s51, s23, 0
	s_add_i32 s49, s52, s26
	global_load_lds_dwordx4 v[178:179], off
	v_lshl_add_u64 v[180:181], s[50:51], 0, v[0:1]
	s_mov_b32 m0, s49
	v_lshl_add_u64 v[210:211], s[24:25], 0, v[132:133]
	global_load_lds_dwordx4 v[180:181], off
	v_lshl_add_u64 v[180:181], s[50:51], 0, v[130:131]
	s_add_i32 m0, s49, 0x2000
	s_nop 0
	global_load_lds_dwordx4 v[180:181], off
	v_lshl_add_u64 v[180:181], s[24:25], 0, v[134:135]
	s_mov_b32 m0, s31
	s_nop 0
	global_load_lds_dwordx4 v[180:181], off
	s_mov_b32 m0, s36
	s_nop 0
	global_load_lds_dwordx4 v[210:211], off
	s_cmp_lg_u32 s48, 0xfffffffe
	s_cbranch_scc1 .Low_1_norm
	s_cmp_eq_u32 s41, 1
	s_cbranch_scc1 .Low_1_norm
	s_waitcnt vmcnt(24)
	s_branch .Low_1_done

.Low_1_done:
	s_waitcnt lgkmcnt(0)
	s_cmp_eq_u32 s48, -2
	s_cbranch_scc1 .Lz0_0_1
	s_setprio 1
	s_barrier
	v_mfma_f32_16x16x32_bf16 v[62:65], v[140:143], v[194:197], v[62:65]
	v_mfma_f32_16x16x32_bf16 v[62:65], v[148:151], v[198:201], v[62:65]
	v_mfma_f32_16x16x32_bf16 v[54:57], v[148:151], v[206:209], v[54:57]
	v_mfma_f32_16x16x32_bf16 v[54:57], v[140:143], v[202:205], v[54:57]
	v_mfma_f32_16x16x32_bf16 v[38:41], v[140:143], v[228:231], v[38:41]
	v_mfma_f32_16x16x32_bf16 v[38:41], v[148:151], v[232:235], v[38:41]
	v_mfma_f32_16x16x32_bf16 v[22:25], v[148:151], v[240:243], v[22:25]
	v_mfma_f32_16x16x32_bf16 v[22:25], v[140:143], v[236:239], v[22:25]
	v_mfma_f32_16x16x32_bf16 v[14:17], v[152:155], v[236:239], v[14:17]
	v_mfma_f32_16x16x32_bf16 v[14:17], v[156:159], v[240:243], v[14:17]
	v_mfma_f32_16x16x32_bf16 v[30:33], v[156:159], v[232:235], v[30:33]
	v_mfma_f32_16x16x32_bf16 v[30:33], v[152:155], v[228:231], v[30:33]
	v_mfma_f32_16x16x32_bf16 v[46:49], v[152:155], v[202:205], v[46:49]
	v_mfma_f32_16x16x32_bf16 v[46:49], v[156:159], v[206:209], v[46:49]
	v_mfma_f32_16x16x32_bf16 v[58:61], v[156:159], v[198:201], v[58:61]
	v_mfma_f32_16x16x32_bf16 v[58:61], v[152:155], v[194:197], v[58:61]
	v_mfma_f32_16x16x32_bf16 v[50:53], v[160:163], v[194:197], v[50:53]
	v_mfma_f32_16x16x32_bf16 v[50:53], v[164:167], v[198:201], v[50:53]
	v_mfma_f32_16x16x32_bf16 v[34:37], v[164:167], v[206:209], v[34:37]
	v_mfma_f32_16x16x32_bf16 v[34:37], v[160:163], v[202:205], v[34:37]
	v_mfma_f32_16x16x32_bf16 v[18:21], v[160:163], v[228:231], v[18:21]
	v_mfma_f32_16x16x32_bf16 v[18:21], v[164:167], v[232:235], v[18:21]
	v_mfma_f32_16x16x32_bf16 v[6:9], v[164:167], v[240:243], v[6:9]
	v_mfma_f32_16x16x32_bf16 v[6:9], v[160:163], v[236:239], v[6:9]
	v_mfma_f32_16x16x32_bf16 v[2:5], v[168:171], v[236:239], v[2:5]
	v_mfma_f32_16x16x32_bf16 v[2:5], v[190:193], v[240:243], v[2:5]
	v_mfma_f32_16x16x32_bf16 v[10:13], v[190:193], v[232:235], v[10:13]
	v_mfma_f32_16x16x32_bf16 v[10:13], v[168:171], v[228:231], v[10:13]
	v_mfma_f32_16x16x32_bf16 v[26:29], v[168:171], v[202:205], v[26:29]
	v_mfma_f32_16x16x32_bf16 v[26:29], v[190:193], v[206:209], v[26:29]
	v_mfma_f32_16x16x32_bf16 v[42:45], v[190:193], v[198:201], v[42:45]
	v_mfma_f32_16x16x32_bf16 v[42:45], v[168:171], v[194:197], v[42:45]
	s_barrier
	s_setprio 0

.Low_4_done:
	s_waitcnt lgkmcnt(0)
	s_cmp_eq_u32 s52, -2
	s_cbranch_scc1 .Lz0_1_0
	s_setprio 1
	s_barrier
	v_mfma_f32_16x16x32_bf16 v[126:129], v[146:149], v[190:193], v[126:129]
	v_mfma_f32_16x16x32_bf16 v[126:129], v[150:153], v[194:197], v[126:129]
	v_mfma_f32_16x16x32_bf16 v[118:121], v[150:153], v[202:205], v[118:121]
	v_mfma_f32_16x16x32_bf16 v[118:121], v[146:149], v[198:201], v[118:121]
	v_mfma_f32_16x16x32_bf16 v[102:105], v[146:149], v[206:209], v[102:105]
	v_mfma_f32_16x16x32_bf16 v[102:105], v[150:153], v[228:231], v[102:105]
	v_mfma_f32_16x16x32_bf16 v[86:89], v[150:153], v[236:239], v[86:89]
	v_mfma_f32_16x16x32_bf16 v[86:89], v[146:149], v[232:235], v[86:89]
	v_mfma_f32_16x16x32_bf16 v[78:81], v[154:157], v[232:235], v[78:81]
	v_mfma_f32_16x16x32_bf16 v[78:81], v[158:161], v[236:239], v[78:81]
	v_mfma_f32_16x16x32_bf16 v[94:97], v[158:161], v[228:231], v[94:97]
	v_mfma_f32_16x16x32_bf16 v[94:97], v[154:157], v[206:209], v[94:97]
	v_mfma_f32_16x16x32_bf16 v[110:113], v[154:157], v[198:201], v[110:113]
	v_mfma_f32_16x16x32_bf16 v[110:113], v[158:161], v[202:205], v[110:113]
	v_mfma_f32_16x16x32_bf16 v[122:125], v[158:161], v[194:197], v[122:125]
	v_mfma_f32_16x16x32_bf16 v[122:125], v[154:157], v[190:193], v[122:125]
	v_mfma_f32_16x16x32_bf16 v[114:117], v[162:165], v[190:193], v[114:117]
	v_mfma_f32_16x16x32_bf16 v[114:117], v[166:169], v[194:197], v[114:117]
	v_mfma_f32_16x16x32_bf16 v[98:101], v[166:169], v[202:205], v[98:101]
	v_mfma_f32_16x16x32_bf16 v[98:101], v[162:165], v[198:201], v[98:101]
	v_mfma_f32_16x16x32_bf16 v[82:85], v[162:165], v[206:209], v[82:85]
	v_mfma_f32_16x16x32_bf16 v[82:85], v[166:169], v[228:231], v[82:85]
	v_mfma_f32_16x16x32_bf16 v[70:73], v[166:169], v[236:239], v[70:73]
	v_mfma_f32_16x16x32_bf16 v[70:73], v[162:165], v[232:235], v[70:73]
	v_mfma_f32_16x16x32_bf16 v[66:69], v[170:173], v[232:235], v[66:69]
	v_mfma_f32_16x16x32_bf16 v[66:69], v[178:181], v[236:239], v[66:69]
	v_mfma_f32_16x16x32_bf16 v[74:77], v[178:181], v[228:231], v[74:77]
	v_mfma_f32_16x16x32_bf16 v[74:77], v[170:173], v[206:209], v[74:77]
	v_mfma_f32_16x16x32_bf16 v[90:93], v[170:173], v[198:201], v[90:93]
	v_mfma_f32_16x16x32_bf16 v[90:93], v[178:181], v[202:205], v[90:93]
	v_mfma_f32_16x16x32_bf16 v[106:109], v[178:181], v[194:197], v[106:109]
	v_mfma_f32_16x16x32_bf16 v[106:109], v[170:173], v[190:193], v[106:109]
	s_barrier
	s_setprio 0
.Lz0_1_0_ret:
	s_add_i32 s53, s53, s38
	v_lshl_add_u64 v[140:141], s[22:23], 0, v[0:1]
	s_mov_b32 m0, s53
	ds_read_b128 v[190:193], v145 offset:16384
	ds_read_b128 v[194:197], v145 offset:17408
	ds_read_b128 v[198:201], v145 offset:18432
	ds_read_b128 v[202:205], v145 offset:19456
	ds_read_b128 v[206:209], v145 offset:20480
	ds_read_b128 v[228:231], v145 offset:21504
	ds_read_b128 v[232:235], v145 offset:22528
	ds_read_b128 v[236:239], v145 offset:23552
	global_load_lds_dwordx4 v[140:141], off
	s_add_i32 m0, s53, 0x2000
	s_add_u32 s54, s22, 0x100000
	v_lshl_add_u64 v[186:187], s[22:23], 0, v[130:131]
	s_addc_u32 s55, s23, 0
	s_add_i32 s53, s56, s38
	global_load_lds_dwordx4 v[186:187], off
	v_lshl_add_u64 v[188:189], s[54:55], 0, v[0:1]
	s_mov_b32 m0, s53
	v_lshl_add_u64 v[210:211], s[24:25], 0, v[132:133]
	global_load_lds_dwordx4 v[188:189], off
	v_lshl_add_u64 v[188:189], s[54:55], 0, v[130:131]
	s_add_i32 m0, s53, 0x2000
	s_nop 0
	global_load_lds_dwordx4 v[188:189], off
	v_lshl_add_u64 v[188:189], s[24:25], 0, v[134:135]
	s_mov_b32 m0, s39
	s_nop 0
	global_load_lds_dwordx4 v[188:189], off
	s_mov_b32 m0, s40
	s_nop 0
	global_load_lds_dwordx4 v[210:211], off
	s_cmp_lg_u32 s52, 0xfffffffe
	s_cbranch_scc1 .Low_3_norm
	s_cmp_eq_u32 s45, 1
	s_cbranch_scc1 .Low_3_norm
	s_waitcnt vmcnt(24)
	s_branch .Low_3_done

.Low_3_done:
	s_waitcnt lgkmcnt(0)
	s_cmp_eq_u32 s52, -2
	s_cbranch_scc1 .Lz0_1_1
	s_setprio 1
	s_barrier
	v_mfma_f32_16x16x32_bf16 v[62:65], v[146:149], v[190:193], v[62:65]
	v_mfma_f32_16x16x32_bf16 v[62:65], v[150:153], v[194:197], v[62:65]
	v_mfma_f32_16x16x32_bf16 v[54:57], v[150:153], v[202:205], v[54:57]
	v_mfma_f32_16x16x32_bf16 v[54:57], v[146:149], v[198:201], v[54:57]
	v_mfma_f32_16x16x32_bf16 v[38:41], v[146:149], v[206:209], v[38:41]
	v_mfma_f32_16x16x32_bf16 v[38:41], v[150:153], v[228:231], v[38:41]
	v_mfma_f32_16x16x32_bf16 v[22:25], v[150:153], v[236:239], v[22:25]
	v_mfma_f32_16x16x32_bf16 v[22:25], v[146:149], v[232:235], v[22:25]
	v_mfma_f32_16x16x32_bf16 v[14:17], v[154:157], v[232:235], v[14:17]
	v_mfma_f32_16x16x32_bf16 v[14:17], v[158:161], v[236:239], v[14:17]
	v_mfma_f32_16x16x32_bf16 v[30:33], v[158:161], v[228:231], v[30:33]
	v_mfma_f32_16x16x32_bf16 v[30:33], v[154:157], v[206:209], v[30:33]
	v_mfma_f32_16x16x32_bf16 v[46:49], v[154:157], v[198:201], v[46:49]
	v_mfma_f32_16x16x32_bf16 v[46:49], v[158:161], v[202:205], v[46:49]
	v_mfma_f32_16x16x32_bf16 v[58:61], v[158:161], v[194:197], v[58:61]
	v_mfma_f32_16x16x32_bf16 v[58:61], v[154:157], v[190:193], v[58:61]
	v_mfma_f32_16x16x32_bf16 v[50:53], v[162:165], v[190:193], v[50:53]
	v_mfma_f32_16x16x32_bf16 v[50:53], v[166:169], v[194:197], v[50:53]
	v_mfma_f32_16x16x32_bf16 v[34:37], v[166:169], v[202:205], v[34:37]
	v_mfma_f32_16x16x32_bf16 v[34:37], v[162:165], v[198:201], v[34:37]
	v_mfma_f32_16x16x32_bf16 v[18:21], v[162:165], v[206:209], v[18:21]
	v_mfma_f32_16x16x32_bf16 v[18:21], v[166:169], v[228:231], v[18:21]
	v_mfma_f32_16x16x32_bf16 v[6:9], v[166:169], v[236:239], v[6:9]
	v_mfma_f32_16x16x32_bf16 v[6:9], v[162:165], v[232:235], v[6:9]
	v_mfma_f32_16x16x32_bf16 v[2:5], v[170:173], v[232:235], v[2:5]
	v_mfma_f32_16x16x32_bf16 v[2:5], v[178:181], v[236:239], v[2:5]
	v_mfma_f32_16x16x32_bf16 v[10:13], v[178:181], v[228:231], v[10:13]
	v_mfma_f32_16x16x32_bf16 v[10:13], v[170:173], v[206:209], v[10:13]
	v_mfma_f32_16x16x32_bf16 v[26:29], v[170:173], v[198:201], v[26:29]
	v_mfma_f32_16x16x32_bf16 v[26:29], v[178:181], v[202:205], v[26:29]
	v_mfma_f32_16x16x32_bf16 v[42:45], v[178:181], v[194:197], v[42:45]
	v_mfma_f32_16x16x32_bf16 v[42:45], v[170:173], v[190:193], v[42:45]
	s_barrier
	s_setprio 0

.Low_6_done:
	s_waitcnt lgkmcnt(0)
	s_cmp_eq_u32 s52, -2
	s_cbranch_scc1 .Lz0_2_0
	s_setprio 1
	s_barrier
	v_mfma_f32_16x16x32_bf16 v[126:129], v[146:149], v[190:193], v[126:129]
	v_mfma_f32_16x16x32_bf16 v[126:129], v[150:153], v[194:197], v[126:129]
	v_mfma_f32_16x16x32_bf16 v[110:113], v[150:153], v[202:205], v[110:113]
	v_mfma_f32_16x16x32_bf16 v[110:113], v[146:149], v[198:201], v[110:113]
	v_mfma_f32_16x16x32_bf16 v[94:97], v[146:149], v[206:209], v[94:97]
	v_mfma_f32_16x16x32_bf16 v[94:97], v[150:153], v[228:231], v[94:97]
	v_mfma_f32_16x16x32_bf16 v[78:81], v[150:153], v[236:239], v[78:81]
	v_mfma_f32_16x16x32_bf16 v[78:81], v[146:149], v[232:235], v[78:81]
	v_mfma_f32_16x16x32_bf16 v[70:73], v[154:157], v[232:235], v[70:73]
	v_mfma_f32_16x16x32_bf16 v[70:73], v[158:161], v[236:239], v[70:73]
	v_mfma_f32_16x16x32_bf16 v[86:89], v[158:161], v[228:231], v[86:89]
	v_mfma_f32_16x16x32_bf16 v[86:89], v[154:157], v[206:209], v[86:89]
	v_mfma_f32_16x16x32_bf16 v[102:105], v[154:157], v[198:201], v[102:105]
	v_mfma_f32_16x16x32_bf16 v[102:105], v[158:161], v[202:205], v[102:105]
	v_mfma_f32_16x16x32_bf16 v[118:121], v[158:161], v[194:197], v[118:121]
	v_mfma_f32_16x16x32_bf16 v[118:121], v[154:157], v[190:193], v[118:121]
	v_mfma_f32_16x16x32_bf16 v[122:125], v[162:165], v[190:193], v[122:125]
	v_mfma_f32_16x16x32_bf16 v[122:125], v[166:169], v[194:197], v[122:125]
	v_mfma_f32_16x16x32_bf16 v[106:109], v[166:169], v[202:205], v[106:109]
	v_mfma_f32_16x16x32_bf16 v[106:109], v[162:165], v[198:201], v[106:109]
	v_mfma_f32_16x16x32_bf16 v[90:93], v[162:165], v[206:209], v[90:93]
	v_mfma_f32_16x16x32_bf16 v[90:93], v[166:169], v[228:231], v[90:93]
	v_mfma_f32_16x16x32_bf16 v[74:77], v[166:169], v[236:239], v[74:77]
	v_mfma_f32_16x16x32_bf16 v[74:77], v[162:165], v[232:235], v[74:77]
	v_mfma_f32_16x16x32_bf16 v[66:69], v[170:173], v[232:235], v[66:69]
	v_mfma_f32_16x16x32_bf16 v[66:69], v[178:181], v[236:239], v[66:69]
	v_mfma_f32_16x16x32_bf16 v[82:85], v[178:181], v[228:231], v[82:85]
	v_mfma_f32_16x16x32_bf16 v[82:85], v[170:173], v[206:209], v[82:85]
	v_mfma_f32_16x16x32_bf16 v[98:101], v[170:173], v[198:201], v[98:101]
	v_mfma_f32_16x16x32_bf16 v[98:101], v[178:181], v[202:205], v[98:101]
	v_mfma_f32_16x16x32_bf16 v[114:117], v[178:181], v[194:197], v[114:117]
	v_mfma_f32_16x16x32_bf16 v[114:117], v[170:173], v[190:193], v[114:117]
	s_barrier
	s_setprio 0
.Lz0_2_0_ret:
	s_add_i32 s53, s53, s26
	v_lshl_add_u64 v[140:141], s[18:19], 0, v[0:1]
	s_mov_b32 m0, s53
	ds_read_b128 v[190:193], v145 offset:16384
	ds_read_b128 v[194:197], v145 offset:17408
	ds_read_b128 v[198:201], v145 offset:18432
	ds_read_b128 v[202:205], v145 offset:19456
	ds_read_b128 v[206:209], v145 offset:20480
	ds_read_b128 v[228:231], v145 offset:21504
	ds_read_b128 v[232:235], v145 offset:22528
	ds_read_b128 v[236:239], v145 offset:23552
	global_load_lds_dwordx4 v[140:141], off
	s_add_i32 m0, s53, 0x2000
	s_add_u32 s54, s18, 0x100000
	v_lshl_add_u64 v[186:187], s[18:19], 0, v[130:131]
	s_addc_u32 s55, s19, 0
	s_add_i32 s53, s56, s26
	global_load_lds_dwordx4 v[186:187], off
	v_lshl_add_u64 v[188:189], s[54:55], 0, v[0:1]
	s_mov_b32 m0, s53
	v_lshl_add_u64 v[210:211], s[22:23], 0, v[132:133]
	global_load_lds_dwordx4 v[188:189], off
	v_lshl_add_u64 v[188:189], s[54:55], 0, v[130:131]
	s_add_i32 m0, s53, 0x2000
	s_nop 0
	global_load_lds_dwordx4 v[188:189], off
	v_lshl_add_u64 v[188:189], s[22:23], 0, v[134:135]
	s_mov_b32 m0, s31
	s_nop 0
	global_load_lds_dwordx4 v[188:189], off
	s_mov_b32 m0, s40
	s_nop 0
	global_load_lds_dwordx4 v[210:211], off
	s_cmp_lg_u32 s52, 0xfffffffe
	s_cbranch_scc1 .Low_5_norm
	s_cmp_eq_u32 s45, 1
	s_cbranch_scc1 .Low_5_norm
	s_waitcnt vmcnt(16)
	s_branch .Low_5_done

.Low_5_done:
	s_waitcnt lgkmcnt(0)
	s_cmp_eq_u32 s52, -2
	s_cbranch_scc1 .Lz0_2_1
	s_setprio 1
	s_barrier
	v_mfma_f32_16x16x32_bf16 v[62:65], v[146:149], v[190:193], v[62:65]
	v_mfma_f32_16x16x32_bf16 v[62:65], v[150:153], v[194:197], v[62:65]
	v_mfma_f32_16x16x32_bf16 v[46:49], v[150:153], v[202:205], v[46:49]
	v_mfma_f32_16x16x32_bf16 v[46:49], v[146:149], v[198:201], v[46:49]
	v_mfma_f32_16x16x32_bf16 v[30:33], v[146:149], v[206:209], v[30:33]
	v_mfma_f32_16x16x32_bf16 v[30:33], v[150:153], v[228:231], v[30:33]
	v_mfma_f32_16x16x32_bf16 v[14:17], v[150:153], v[236:239], v[14:17]
	v_mfma_f32_16x16x32_bf16 v[14:17], v[146:149], v[232:235], v[14:17]
	v_mfma_f32_16x16x32_bf16 v[6:9], v[154:157], v[232:235], v[6:9]
	v_mfma_f32_16x16x32_bf16 v[6:9], v[158:161], v[236:239], v[6:9]
	v_mfma_f32_16x16x32_bf16 v[22:25], v[158:161], v[228:231], v[22:25]
	v_mfma_f32_16x16x32_bf16 v[22:25], v[154:157], v[206:209], v[22:25]
	v_mfma_f32_16x16x32_bf16 v[38:41], v[154:157], v[198:201], v[38:41]
	v_mfma_f32_16x16x32_bf16 v[38:41], v[158:161], v[202:205], v[38:41]
	v_mfma_f32_16x16x32_bf16 v[54:57], v[158:161], v[194:197], v[54:57]
	v_mfma_f32_16x16x32_bf16 v[54:57], v[154:157], v[190:193], v[54:57]
	v_mfma_f32_16x16x32_bf16 v[58:61], v[162:165], v[190:193], v[58:61]
	v_mfma_f32_16x16x32_bf16 v[58:61], v[166:169], v[194:197], v[58:61]
	v_mfma_f32_16x16x32_bf16 v[42:45], v[166:169], v[202:205], v[42:45]
	v_mfma_f32_16x16x32_bf16 v[42:45], v[162:165], v[198:201], v[42:45]
	v_mfma_f32_16x16x32_bf16 v[26:29], v[162:165], v[206:209], v[26:29]
	v_mfma_f32_16x16x32_bf16 v[26:29], v[166:169], v[228:231], v[26:29]
	v_mfma_f32_16x16x32_bf16 v[10:13], v[166:169], v[236:239], v[10:13]
	v_mfma_f32_16x16x32_bf16 v[10:13], v[162:165], v[232:235], v[10:13]
	v_mfma_f32_16x16x32_bf16 v[2:5], v[170:173], v[232:235], v[2:5]
	v_mfma_f32_16x16x32_bf16 v[2:5], v[178:181], v[236:239], v[2:5]
	v_mfma_f32_16x16x32_bf16 v[18:21], v[178:181], v[228:231], v[18:21]
	v_mfma_f32_16x16x32_bf16 v[18:21], v[170:173], v[206:209], v[18:21]
	v_mfma_f32_16x16x32_bf16 v[34:37], v[170:173], v[198:201], v[34:37]
	v_mfma_f32_16x16x32_bf16 v[34:37], v[178:181], v[202:205], v[34:37]
	v_mfma_f32_16x16x32_bf16 v[50:53], v[178:181], v[194:197], v[50:53]
	v_mfma_f32_16x16x32_bf16 v[50:53], v[170:173], v[190:193], v[50:53]
	s_barrier
	s_setprio 0

.Low_8_done:
	s_waitcnt lgkmcnt(0)
	s_cmp_eq_u32 s48, -2
	s_cbranch_scc1 .Lz0_3_0
	s_setprio 1
	s_barrier
	v_mfma_f32_16x16x32_bf16 v[126:129], v[146:149], v[190:193], v[126:129]
	v_mfma_f32_16x16x32_bf16 v[126:129], v[150:153], v[194:197], v[126:129]
	v_mfma_f32_16x16x32_bf16 v[118:121], v[150:153], v[202:205], v[118:121]
	v_mfma_f32_16x16x32_bf16 v[118:121], v[146:149], v[198:201], v[118:121]
	v_mfma_f32_16x16x32_bf16 v[102:105], v[146:149], v[206:209], v[102:105]
	v_mfma_f32_16x16x32_bf16 v[102:105], v[150:153], v[228:231], v[102:105]
	v_mfma_f32_16x16x32_bf16 v[86:89], v[150:153], v[236:239], v[86:89]
	v_mfma_f32_16x16x32_bf16 v[86:89], v[146:149], v[232:235], v[86:89]
	v_mfma_f32_16x16x32_bf16 v[78:81], v[154:157], v[232:235], v[78:81]
	v_mfma_f32_16x16x32_bf16 v[78:81], v[158:161], v[236:239], v[78:81]
	v_mfma_f32_16x16x32_bf16 v[94:97], v[158:161], v[228:231], v[94:97]
	v_mfma_f32_16x16x32_bf16 v[94:97], v[154:157], v[206:209], v[94:97]
	v_mfma_f32_16x16x32_bf16 v[110:113], v[154:157], v[198:201], v[110:113]
	v_mfma_f32_16x16x32_bf16 v[110:113], v[158:161], v[202:205], v[110:113]
	v_mfma_f32_16x16x32_bf16 v[122:125], v[158:161], v[194:197], v[122:125]
	v_mfma_f32_16x16x32_bf16 v[122:125], v[154:157], v[190:193], v[122:125]
	v_mfma_f32_16x16x32_bf16 v[114:117], v[162:165], v[190:193], v[114:117]
	v_mfma_f32_16x16x32_bf16 v[114:117], v[166:169], v[194:197], v[114:117]
	v_mfma_f32_16x16x32_bf16 v[98:101], v[166:169], v[202:205], v[98:101]
	v_mfma_f32_16x16x32_bf16 v[98:101], v[162:165], v[198:201], v[98:101]
	v_mfma_f32_16x16x32_bf16 v[82:85], v[162:165], v[206:209], v[82:85]
	v_mfma_f32_16x16x32_bf16 v[82:85], v[166:169], v[228:231], v[82:85]
	v_mfma_f32_16x16x32_bf16 v[70:73], v[166:169], v[236:239], v[70:73]
	v_mfma_f32_16x16x32_bf16 v[70:73], v[162:165], v[232:235], v[70:73]
	v_mfma_f32_16x16x32_bf16 v[66:69], v[170:173], v[232:235], v[66:69]
	v_mfma_f32_16x16x32_bf16 v[66:69], v[178:181], v[236:239], v[66:69]
	v_mfma_f32_16x16x32_bf16 v[74:77], v[178:181], v[228:231], v[74:77]
	v_mfma_f32_16x16x32_bf16 v[74:77], v[170:173], v[206:209], v[74:77]
	v_mfma_f32_16x16x32_bf16 v[90:93], v[170:173], v[198:201], v[90:93]
	v_mfma_f32_16x16x32_bf16 v[90:93], v[178:181], v[202:205], v[90:93]
	v_mfma_f32_16x16x32_bf16 v[106:109], v[178:181], v[194:197], v[106:109]
	v_mfma_f32_16x16x32_bf16 v[106:109], v[170:173], v[190:193], v[106:109]
	s_barrier
	s_setprio 0
.Lz0_3_0_ret:
	s_add_i32 s14, s49, s26
	v_lshl_add_u64 v[140:141], s[18:19], 0, v[0:1]
	s_mov_b32 m0, s14
	ds_read_b128 v[190:193], v145 offset:16384
	ds_read_b128 v[194:197], v145 offset:17408
	ds_read_b128 v[198:201], v145 offset:18432
	ds_read_b128 v[202:205], v145 offset:19456
	ds_read_b128 v[206:209], v145 offset:20480
	ds_read_b128 v[228:231], v145 offset:21504
	ds_read_b128 v[232:235], v145 offset:22528
	ds_read_b128 v[236:239], v145 offset:23552
	global_load_lds_dwordx4 v[140:141], off
	s_add_i32 m0, s14, 0x2000
	s_add_u32 s14, s18, 0x2b0000
	v_lshl_add_u64 v[186:187], s[18:19], 0, v[130:131]
	s_addc_u32 s15, s19, 0
	s_add_i32 s49, s50, s26
	global_load_lds_dwordx4 v[186:187], off
	v_lshl_add_u64 v[188:189], s[14:15], 0, v[0:1]
	s_mov_b32 m0, s49
	v_lshl_add_u64 v[210:211], s[22:23], 0, v[132:133]
	global_load_lds_dwordx4 v[188:189], off
	v_lshl_add_u64 v[188:189], s[14:15], 0, v[130:131]
	s_add_i32 m0, s49, 0x2000
	s_nop 0
	global_load_lds_dwordx4 v[188:189], off
	v_lshl_add_u64 v[188:189], s[22:23], 0, v[134:135]
	s_mov_b32 m0, s31
	s_nop 0
	global_load_lds_dwordx4 v[188:189], off
	s_mov_b32 m0, s36
	s_nop 0
	global_load_lds_dwordx4 v[210:211], off
	s_cmp_lg_u32 s48, 0xfffffffe
	s_cbranch_scc1 .Low_7_norm
	s_cmp_eq_u32 s41, 1
	s_cbranch_scc1 .Low_7_norm
	s_waitcnt vmcnt(24)
	s_branch .Low_7_done

.Low_7_done:
	s_waitcnt lgkmcnt(0)
	s_cmp_eq_u32 s48, -2
	s_cbranch_scc1 .Lz0_3_1
	s_setprio 1
	s_barrier
	v_mfma_f32_16x16x32_bf16 v[62:65], v[146:149], v[190:193], v[62:65]
	v_mfma_f32_16x16x32_bf16 v[62:65], v[150:153], v[194:197], v[62:65]
	v_mfma_f32_16x16x32_bf16 v[54:57], v[150:153], v[202:205], v[54:57]
	v_mfma_f32_16x16x32_bf16 v[54:57], v[146:149], v[198:201], v[54:57]
	v_mfma_f32_16x16x32_bf16 v[38:41], v[146:149], v[206:209], v[38:41]
	v_mfma_f32_16x16x32_bf16 v[38:41], v[150:153], v[228:231], v[38:41]
	v_mfma_f32_16x16x32_bf16 v[22:25], v[150:153], v[236:239], v[22:25]
	v_mfma_f32_16x16x32_bf16 v[22:25], v[146:149], v[232:235], v[22:25]
	v_mfma_f32_16x16x32_bf16 v[14:17], v[154:157], v[232:235], v[14:17]
	v_mfma_f32_16x16x32_bf16 v[14:17], v[158:161], v[236:239], v[14:17]
	v_mfma_f32_16x16x32_bf16 v[30:33], v[158:161], v[228:231], v[30:33]
	v_mfma_f32_16x16x32_bf16 v[30:33], v[154:157], v[206:209], v[30:33]
	v_mfma_f32_16x16x32_bf16 v[46:49], v[154:157], v[198:201], v[46:49]
	v_mfma_f32_16x16x32_bf16 v[46:49], v[158:161], v[202:205], v[46:49]
	v_mfma_f32_16x16x32_bf16 v[58:61], v[158:161], v[194:197], v[58:61]
	v_mfma_f32_16x16x32_bf16 v[58:61], v[154:157], v[190:193], v[58:61]
	v_mfma_f32_16x16x32_bf16 v[50:53], v[162:165], v[190:193], v[50:53]
	v_mfma_f32_16x16x32_bf16 v[50:53], v[166:169], v[194:197], v[50:53]
	v_mfma_f32_16x16x32_bf16 v[34:37], v[166:169], v[202:205], v[34:37]
	v_mfma_f32_16x16x32_bf16 v[34:37], v[162:165], v[198:201], v[34:37]
	v_mfma_f32_16x16x32_bf16 v[18:21], v[162:165], v[206:209], v[18:21]
	v_mfma_f32_16x16x32_bf16 v[18:21], v[166:169], v[228:231], v[18:21]
	v_mfma_f32_16x16x32_bf16 v[6:9], v[166:169], v[236:239], v[6:9]
	v_mfma_f32_16x16x32_bf16 v[6:9], v[162:165], v[232:235], v[6:9]
	v_mfma_f32_16x16x32_bf16 v[2:5], v[170:173], v[232:235], v[2:5]
	v_mfma_f32_16x16x32_bf16 v[2:5], v[178:181], v[236:239], v[2:5]
	v_mfma_f32_16x16x32_bf16 v[10:13], v[178:181], v[228:231], v[10:13]
	v_mfma_f32_16x16x32_bf16 v[10:13], v[170:173], v[206:209], v[10:13]
	v_mfma_f32_16x16x32_bf16 v[26:29], v[170:173], v[198:201], v[26:29]
	v_mfma_f32_16x16x32_bf16 v[26:29], v[178:181], v[202:205], v[26:29]
	v_mfma_f32_16x16x32_bf16 v[42:45], v[178:181], v[194:197], v[42:45]
	v_mfma_f32_16x16x32_bf16 v[42:45], v[170:173], v[190:193], v[42:45]
	s_barrier
	s_setprio 0
